# P2 q-projection rope-tile epilogue: cos/sin loads pipelined in three register sets, results kept in consumed accumulators, sixteen 16-byte stores at the end; on top of v126
# speedup vs baseline: 1.0089x; 1.0004x over previous
; __device__ __forceinline__ unsigned cvt_pk_bf16(float lo, float hi) { unsigned r; asm volatile("v_cvt_pk_bf16_f32 %0, %1, %2" : "=v"(r) : "v"(lo), "v"(hi)); return r; }
; #define EPI_FENCE() asm volatile("" ::: "memory")
; __device__ __forceinline__ u32x4 pack8(f32x4 a, f32x4 b) { u32x4 w; w.x = cvt_pk_bf16(a[0], a[1]); w.y = cvt_pk_bf16(a[2], a[3]); w.z = cvt_pk_bf16(b[0], b[1]); w.w = cvt_pk_bf16(b[2], b[3]); return w; }
;   __device__ __forceinline__ void operator()(const AccT& acc, const pg8::Unit& u, int wr, int wc, int fr, int fq) const {
;     ...
;         for (int m = 0; m < 4; ++m) { const int row = row0 + ai * 128 + m * 16; const float r = rsqrtf(rr[ai][m] * (1.f / 512.f) + NORM_EPS);
; #pragma unroll
;           for (int bj = 0; bj < 2; ++bj) *(u32x4*)(qn + (size_t)row * 1024 + pn * 256 + bj * 128 + cw) = pack8(acc[ai][bj][m][0] * r, acc[ai][bj][m][1] * r);
;           EPI_FENCE(); }
;     } else {
;       const int head = 4 * (pn - 4) + wc;
; #pragma unroll
;       for (int ai = 0; ai < 2; ++ai)
; #pragma unroll
;         for (int m = 0; m < 4; ++m) { const int row = row0 + ai * 128 + m * 16; const float r = rsqrtf(rr[ai][m] * (1.f / 512.f) + NORM_EPS);
;           bf16_t* p = qr + (size_t)row * 512 + head * 64 + 8 * fq;
; #pragma unroll
;           for (int n = 0; n < 2; ++n) { const f32x4 c = *(const f32x4*)(cos_r + (size_t)row * 32 + 8 * fq + 4 * n), s = *(const f32x4*)(sin_r + (size_t)row * 32 + 8 * fq + 4 * n);
;             const f32x4 a = acc[ai][0][m][n] * r, b = acc[ai][1][m][n] * r, lo = a * c - b * s, hi = a * s + b * c;
;             u32x2 w0, w1; w0.x = cvt_pk_bf16(lo[0], lo[1]); w0.y = cvt_pk_bf16(lo[2], lo[3]); w1.x = cvt_pk_bf16(hi[0], hi[1]); w1.y = cvt_pk_bf16(hi[2], hi[3]);
;             *(u32x2*)(p + 4 * n) = w0; *(u32x2*)(p + 32 + 4 * n) = w1; }
.LBB0_279:
	v_lshl_add_u32 v170, s22, 8, v185
	v_ashrrev_i32_e32 v171, 31, v170
	v_or_b32_e32 v168, 16, v170
	v_or_b32_e32 v166, 32, v170
	v_or_b32_e32 v164, 48, v170
	v_lshl_add_u64 v[156:157], v[170:171], 2, s[10:11]
	v_ashrrev_i32_e32 v169, 31, v168
	v_ashrrev_i32_e32 v167, 31, v166
	v_ashrrev_i32_e32 v165, 31, v164
	v_lshl_add_u64 v[158:159], v[168:169], 2, s[10:11]
	v_lshl_add_u64 v[160:161], v[166:167], 2, s[10:11]
	v_lshl_add_u64 v[162:163], v[164:165], 2, s[10:11]
	global_load_dword v155, v[156:157], off
	global_load_dword v195, v[156:157], off offset:512
	global_load_dword v197, v[158:159], off
	global_load_dword v198, v[160:161], off
	global_load_dword v199, v[162:163], off
	global_load_dword v206, v[156:157], off offset:576
	global_load_dword v194, v[156:157], off offset:640
	global_load_dword v193, v[156:157], off offset:704
	s_lshl_b32 s46, s89, 8
	v_add_u32_e32 v162, 0x80, v170
	v_add_u32_e32 v160, 0x90, v170
	v_add_u32_e32 v158, 0xa0, v170
	v_add_u32_e32 v156, 0xb0, v170
	s_mov_b64 s[48:49], -1
	s_cmp_gt_i32 s89, 3
	v_ashrrev_i32_e32 v163, 31, v162
	v_ashrrev_i32_e32 v161, 31, v160
	v_ashrrev_i32_e32 v159, 31, v158
	v_ashrrev_i32_e32 v157, 31, v156
	s_waitcnt vmcnt(0)
	v_fmamk_f32 v204, v155, 0x3b000000, v191
	v_fmamk_f32 v196, v195, 0x3b000000, v191
	v_fmamk_f32 v202, v197, 0x3b000000, v191
	v_fmamk_f32 v200, v198, 0x3b000000, v191
	v_fmamk_f32 v198, v199, 0x3b000000, v191
	v_cmp_gt_f32_e64 s[0:1], s85, v204
	v_mul_f32_e32 v205, 0x4b800000, v204
	v_cmp_gt_f32_e32 vcc, s85, v196
	v_mul_f32_e32 v197, 0x4b800000, v196
	v_cmp_gt_f32_e64 s[8:9], s85, v202
	v_mul_f32_e32 v203, 0x4b800000, v202
	v_cmp_gt_f32_e64 s[6:7], s85, v200
	v_mul_f32_e32 v201, 0x4b800000, v200
	v_cmp_gt_f32_e64 s[4:5], s85, v198
	v_mul_f32_e32 v199, 0x4b800000, v198
	v_fmamk_f32 v195, v206, 0x3b000000, v191
	s_cbranch_scc0 .LBB0_281
	s_add_i32 s22, s84, s46
	s_lshl_b64 s[48:49], s[22:23], 1
	v_mov_b32_e32 v155, v139
	v_lshlrev_b64 v[230:231], 7, v[170:171]
	v_lshl_add_u64 v[214:215], v[142:143], 0, v[230:231]
	v_lshl_add_u64 v[216:217], v[140:141], 0, v[230:231]
	global_load_dwordx4 v[206:209], v[214:215], off
	global_load_dwordx4 v[210:213], v[216:217], off
	global_load_dwordx4 v[234:237], v[214:215], off offset:16
	global_load_dwordx4 v[238:241], v[216:217], off offset:16
	v_lshlrev_b64 v[230:231], 7, v[168:169]
	v_lshl_add_u64 v[250:251], v[142:143], 0, v[230:231]
	v_lshl_add_u64 v[252:253], v[140:141], 0, v[230:231]
	global_load_dwordx4 v[242:245], v[250:251], off
	global_load_dwordx4 v[246:249], v[252:253], off
	v_cmp_gt_f32_e32 vcc, s85, v204
	v_mul_f32_e32 v220, 0x4b800000, v204
	v_cndmask_b32_e32 v220, v204, v220, vcc
	v_rsq_f32_e32 v220, v220
	v_mul_f32_e32 v221, 0x45800000, v220
	v_cndmask_b32_e32 v220, v220, v221, vcc
	v_pk_mul_f32 v[222:223], v[124:125], v[220:221] op_sel_hi:[1,0]
	v_pk_mul_f32 v[224:225], v[126:127], v[220:221] op_sel_hi:[1,0]
	v_pk_mul_f32 v[228:229], v[116:117], v[220:221] op_sel_hi:[1,0]
	v_pk_mul_f32 v[226:227], v[118:119], v[220:221] op_sel_hi:[1,0]
	s_waitcnt vmcnt(4)
	v_pk_mul_f32 v[230:231], v[228:229], v[206:207]
	v_pk_mul_f32 v[232:233], v[226:227], v[208:209]
	v_pk_mul_f32 v[206:207], v[222:223], v[206:207]
	v_pk_mul_f32 v[208:209], v[224:225], v[208:209]
	v_pk_fma_f32 v[224:225], v[224:225], v[212:213], v[232:233] neg_lo:[0,0,1] neg_hi:[0,0,1]
	v_pk_fma_f32 v[222:223], v[222:223], v[210:211], v[230:231] neg_lo:[0,0,1] neg_hi:[0,0,1]
	v_pk_fma_f32 v[206:207], v[228:229], v[210:211], v[206:207]
	v_pk_fma_f32 v[208:209], v[226:227], v[212:213], v[208:209]
	v_cvt_pk_bf16_f32 v124, v222, v223
	v_cvt_pk_bf16_f32 v125, v224, v225
	v_cvt_pk_bf16_f32 v116, v206, v207
	v_cvt_pk_bf16_f32 v117, v208, v209
	global_load_dwordx4 v[206:209], v[250:251], off offset:16
	global_load_dwordx4 v[210:213], v[252:253], off offset:16
	v_pk_mul_f32 v[222:223], v[120:121], v[220:221] op_sel_hi:[1,0]
	v_pk_mul_f32 v[224:225], v[122:123], v[220:221] op_sel_hi:[1,0]
	v_pk_mul_f32 v[228:229], v[112:113], v[220:221] op_sel_hi:[1,0]
	v_pk_mul_f32 v[226:227], v[114:115], v[220:221] op_sel_hi:[1,0]
	s_waitcnt vmcnt(4)
	v_pk_mul_f32 v[230:231], v[228:229], v[234:235]
	v_pk_mul_f32 v[232:233], v[226:227], v[236:237]
	v_pk_mul_f32 v[234:235], v[222:223], v[234:235]
	v_pk_mul_f32 v[236:237], v[224:225], v[236:237]
	v_pk_fma_f32 v[224:225], v[224:225], v[240:241], v[232:233] neg_lo:[0,0,1] neg_hi:[0,0,1]
	v_pk_fma_f32 v[222:223], v[222:223], v[238:239], v[230:231] neg_lo:[0,0,1] neg_hi:[0,0,1]
	v_pk_fma_f32 v[234:235], v[228:229], v[238:239], v[234:235]
	v_pk_fma_f32 v[236:237], v[226:227], v[240:241], v[236:237]
	v_cvt_pk_bf16_f32 v126, v222, v223
	v_cvt_pk_bf16_f32 v127, v224, v225
	v_cvt_pk_bf16_f32 v118, v234, v235
	v_cvt_pk_bf16_f32 v119, v236, v237
	v_lshlrev_b64 v[230:231], 7, v[166:167]
	v_lshl_add_u64 v[214:215], v[142:143], 0, v[230:231]
	v_lshl_add_u64 v[216:217], v[140:141], 0, v[230:231]
	global_load_dwordx4 v[234:237], v[214:215], off
	global_load_dwordx4 v[238:241], v[216:217], off
	v_cmp_gt_f32_e32 vcc, s85, v202
	v_mul_f32_e32 v220, 0x4b800000, v202
	v_cndmask_b32_e32 v220, v202, v220, vcc
	v_rsq_f32_e32 v220, v220
	v_mul_f32_e32 v221, 0x45800000, v220
	v_cndmask_b32_e32 v220, v220, v221, vcc
	v_pk_mul_f32 v[222:223], v[108:109], v[220:221] op_sel_hi:[1,0]
	v_pk_mul_f32 v[224:225], v[110:111], v[220:221] op_sel_hi:[1,0]
	v_pk_mul_f32 v[228:229], v[100:101], v[220:221] op_sel_hi:[1,0]
	v_pk_mul_f32 v[226:227], v[102:103], v[220:221] op_sel_hi:[1,0]
	s_waitcnt vmcnt(4)
; __device__ __forceinline__ unsigned cvt_pk_bf16(float lo, float hi) { unsigned r; asm volatile("v_cvt_pk_bf16_f32 %0, %1, %2" : "=v"(r) : "v"(lo), "v"(hi)); return r; }
; #define EPI_FENCE() asm volatile("" ::: "memory")
;   __device__ __forceinline__ void operator()(const AccT& acc, const pg8::Unit& u, int wr, int wc, int fr, int fq) const {
;     ...
;         for (int m = 0; m < 4; ++m) { const int row = row0 + ai * 128 + m * 16; const float r = rsqrtf(rr[ai][m] * (1.f / 512.f) + NORM_EPS);
;           bf16_t* p = qr + (size_t)row * 512 + head * 64 + 8 * fq;
; #pragma unroll
;           for (int n = 0; n < 2; ++n) { const f32x4 c = *(const f32x4*)(cos_r + (size_t)row * 32 + 8 * fq + 4 * n), s = *(const f32x4*)(sin_r + (size_t)row * 32 + 8 * fq + 4 * n);
;             const f32x4 a = acc[ai][0][m][n] * r, b = acc[ai][1][m][n] * r, lo = a * c - b * s, hi = a * s + b * c;
;             u32x2 w0, w1; w0.x = cvt_pk_bf16(lo[0], lo[1]); w0.y = cvt_pk_bf16(lo[2], lo[3]); w1.x = cvt_pk_bf16(hi[0], hi[1]); w1.y = cvt_pk_bf16(hi[2], hi[3]);
;             *(u32x2*)(p + 4 * n) = w0; *(u32x2*)(p + 32 + 4 * n) = w1; }
;           EPI_FENCE(); }
	v_pk_mul_f32 v[230:231], v[228:229], v[242:243]
	v_pk_mul_f32 v[232:233], v[226:227], v[244:245]
	v_pk_mul_f32 v[242:243], v[222:223], v[242:243]
	v_pk_mul_f32 v[244:245], v[224:225], v[244:245]
	v_pk_fma_f32 v[224:225], v[224:225], v[248:249], v[232:233] neg_lo:[0,0,1] neg_hi:[0,0,1]
	v_pk_fma_f32 v[222:223], v[222:223], v[246:247], v[230:231] neg_lo:[0,0,1] neg_hi:[0,0,1]
	v_pk_fma_f32 v[242:243], v[228:229], v[246:247], v[242:243]
	v_pk_fma_f32 v[244:245], v[226:227], v[248:249], v[244:245]
	v_cvt_pk_bf16_f32 v108, v222, v223
	v_cvt_pk_bf16_f32 v109, v224, v225
	v_cvt_pk_bf16_f32 v100, v242, v243
	v_cvt_pk_bf16_f32 v101, v244, v245
	global_load_dwordx4 v[242:245], v[214:215], off offset:16
	global_load_dwordx4 v[246:249], v[216:217], off offset:16
	v_pk_mul_f32 v[222:223], v[104:105], v[220:221] op_sel_hi:[1,0]
	v_pk_mul_f32 v[224:225], v[106:107], v[220:221] op_sel_hi:[1,0]
	v_pk_mul_f32 v[228:229], v[96:97], v[220:221] op_sel_hi:[1,0]
	v_pk_mul_f32 v[226:227], v[98:99], v[220:221] op_sel_hi:[1,0]
	s_waitcnt vmcnt(4)
	v_pk_mul_f32 v[230:231], v[228:229], v[206:207]
	v_pk_mul_f32 v[232:233], v[226:227], v[208:209]
	v_pk_mul_f32 v[206:207], v[222:223], v[206:207]
	v_pk_mul_f32 v[208:209], v[224:225], v[208:209]
	v_pk_fma_f32 v[224:225], v[224:225], v[212:213], v[232:233] neg_lo:[0,0,1] neg_hi:[0,0,1]
	v_pk_fma_f32 v[222:223], v[222:223], v[210:211], v[230:231] neg_lo:[0,0,1] neg_hi:[0,0,1]
	v_pk_fma_f32 v[206:207], v[228:229], v[210:211], v[206:207]
	v_pk_fma_f32 v[208:209], v[226:227], v[212:213], v[208:209]
	v_cvt_pk_bf16_f32 v110, v222, v223
	v_cvt_pk_bf16_f32 v111, v224, v225
	v_cvt_pk_bf16_f32 v102, v206, v207
	v_cvt_pk_bf16_f32 v103, v208, v209
	v_lshlrev_b64 v[230:231], 7, v[164:165]
	v_lshl_add_u64 v[250:251], v[142:143], 0, v[230:231]
	v_lshl_add_u64 v[252:253], v[140:141], 0, v[230:231]
	global_load_dwordx4 v[206:209], v[250:251], off
	global_load_dwordx4 v[210:213], v[252:253], off
	v_cmp_gt_f32_e32 vcc, s85, v200
	v_mul_f32_e32 v220, 0x4b800000, v200
	v_cndmask_b32_e32 v220, v200, v220, vcc
	v_rsq_f32_e32 v220, v220
	v_mul_f32_e32 v221, 0x45800000, v220
	v_cndmask_b32_e32 v220, v220, v221, vcc
	v_pk_mul_f32 v[222:223], v[92:93], v[220:221] op_sel_hi:[1,0]
	v_pk_mul_f32 v[224:225], v[94:95], v[220:221] op_sel_hi:[1,0]
	v_pk_mul_f32 v[228:229], v[84:85], v[220:221] op_sel_hi:[1,0]
	v_pk_mul_f32 v[226:227], v[86:87], v[220:221] op_sel_hi:[1,0]
	s_waitcnt vmcnt(4)
	v_pk_mul_f32 v[230:231], v[228:229], v[234:235]
	v_pk_mul_f32 v[232:233], v[226:227], v[236:237]
	v_pk_mul_f32 v[234:235], v[222:223], v[234:235]
	v_pk_mul_f32 v[236:237], v[224:225], v[236:237]
	v_pk_fma_f32 v[224:225], v[224:225], v[240:241], v[232:233] neg_lo:[0,0,1] neg_hi:[0,0,1]
	v_pk_fma_f32 v[222:223], v[222:223], v[238:239], v[230:231] neg_lo:[0,0,1] neg_hi:[0,0,1]
	v_pk_fma_f32 v[234:235], v[228:229], v[238:239], v[234:235]
	v_pk_fma_f32 v[236:237], v[226:227], v[240:241], v[236:237]
	v_cvt_pk_bf16_f32 v92, v222, v223
	v_cvt_pk_bf16_f32 v93, v224, v225
	v_cvt_pk_bf16_f32 v84, v234, v235
	v_cvt_pk_bf16_f32 v85, v236, v237
	global_load_dwordx4 v[234:237], v[250:251], off offset:16
	global_load_dwordx4 v[238:241], v[252:253], off offset:16
	v_pk_mul_f32 v[222:223], v[88:89], v[220:221] op_sel_hi:[1,0]
	v_pk_mul_f32 v[224:225], v[90:91], v[220:221] op_sel_hi:[1,0]
	v_pk_mul_f32 v[228:229], v[80:81], v[220:221] op_sel_hi:[1,0]
	v_pk_mul_f32 v[226:227], v[82:83], v[220:221] op_sel_hi:[1,0]
	s_waitcnt vmcnt(4)
	v_pk_mul_f32 v[230:231], v[228:229], v[242:243]
	v_pk_mul_f32 v[232:233], v[226:227], v[244:245]
	v_pk_mul_f32 v[242:243], v[222:223], v[242:243]
	v_pk_mul_f32 v[244:245], v[224:225], v[244:245]
	v_pk_fma_f32 v[224:225], v[224:225], v[248:249], v[232:233] neg_lo:[0,0,1] neg_hi:[0,0,1]
	v_pk_fma_f32 v[222:223], v[222:223], v[246:247], v[230:231] neg_lo:[0,0,1] neg_hi:[0,0,1]
	v_pk_fma_f32 v[242:243], v[228:229], v[246:247], v[242:243]
	v_pk_fma_f32 v[244:245], v[226:227], v[248:249], v[244:245]
	v_cvt_pk_bf16_f32 v94, v222, v223
	v_cvt_pk_bf16_f32 v95, v224, v225
	v_cvt_pk_bf16_f32 v86, v242, v243
	v_cvt_pk_bf16_f32 v87, v244, v245
	v_lshlrev_b64 v[230:231], 7, v[162:163]
	v_lshl_add_u64 v[214:215], v[142:143], 0, v[230:231]
	v_lshl_add_u64 v[216:217], v[140:141], 0, v[230:231]
	global_load_dwordx4 v[242:245], v[214:215], off
	global_load_dwordx4 v[246:249], v[216:217], off
	v_cmp_gt_f32_e32 vcc, s85, v198
	v_mul_f32_e32 v220, 0x4b800000, v198
	v_cndmask_b32_e32 v220, v198, v220, vcc
	v_rsq_f32_e32 v220, v220
	v_mul_f32_e32 v221, 0x45800000, v220
	v_cndmask_b32_e32 v220, v220, v221, vcc
	v_pk_mul_f32 v[222:223], v[76:77], v[220:221] op_sel_hi:[1,0]
	v_pk_mul_f32 v[224:225], v[78:79], v[220:221] op_sel_hi:[1,0]
	v_pk_mul_f32 v[228:229], v[68:69], v[220:221] op_sel_hi:[1,0]
	v_pk_mul_f32 v[226:227], v[70:71], v[220:221] op_sel_hi:[1,0]
	s_waitcnt vmcnt(4)
	v_pk_mul_f32 v[230:231], v[228:229], v[206:207]
	v_pk_mul_f32 v[232:233], v[226:227], v[208:209]
	v_pk_mul_f32 v[206:207], v[222:223], v[206:207]
	v_pk_mul_f32 v[208:209], v[224:225], v[208:209]
	v_pk_fma_f32 v[224:225], v[224:225], v[212:213], v[232:233] neg_lo:[0,0,1] neg_hi:[0,0,1]
	v_pk_fma_f32 v[222:223], v[222:223], v[210:211], v[230:231] neg_lo:[0,0,1] neg_hi:[0,0,1]
	v_pk_fma_f32 v[206:207], v[228:229], v[210:211], v[206:207]
	v_pk_fma_f32 v[208:209], v[226:227], v[212:213], v[208:209]
	v_cvt_pk_bf16_f32 v76, v222, v223
	v_cvt_pk_bf16_f32 v77, v224, v225
	v_cvt_pk_bf16_f32 v68, v206, v207
	v_cvt_pk_bf16_f32 v69, v208, v209
	global_load_dwordx4 v[206:209], v[214:215], off offset:16
	global_load_dwordx4 v[210:213], v[216:217], off offset:16
	v_pk_mul_f32 v[222:223], v[72:73], v[220:221] op_sel_hi:[1,0]
	v_pk_mul_f32 v[224:225], v[74:75], v[220:221] op_sel_hi:[1,0]
	v_pk_mul_f32 v[228:229], v[64:65], v[220:221] op_sel_hi:[1,0]
	v_pk_mul_f32 v[226:227], v[66:67], v[220:221] op_sel_hi:[1,0]
	s_waitcnt vmcnt(4)
; __device__ __forceinline__ unsigned cvt_pk_bf16(float lo, float hi) { unsigned r; asm volatile("v_cvt_pk_bf16_f32 %0, %1, %2" : "=v"(r) : "v"(lo), "v"(hi)); return r; }
; #define EPI_FENCE() asm volatile("" ::: "memory")
;   __device__ __forceinline__ void operator()(const AccT& acc, const pg8::Unit& u, int wr, int wc, int fr, int fq) const {
;     ...
;         for (int m = 0; m < 4; ++m) { const int row = row0 + ai * 128 + m * 16; const float r = rsqrtf(rr[ai][m] * (1.f / 512.f) + NORM_EPS);
;           bf16_t* p = qr + (size_t)row * 512 + head * 64 + 8 * fq;
; #pragma unroll
;           for (int n = 0; n < 2; ++n) { const f32x4 c = *(const f32x4*)(cos_r + (size_t)row * 32 + 8 * fq + 4 * n), s = *(const f32x4*)(sin_r + (size_t)row * 32 + 8 * fq + 4 * n);
;             const f32x4 a = acc[ai][0][m][n] * r, b = acc[ai][1][m][n] * r, lo = a * c - b * s, hi = a * s + b * c;
;             u32x2 w0, w1; w0.x = cvt_pk_bf16(lo[0], lo[1]); w0.y = cvt_pk_bf16(lo[2], lo[3]); w1.x = cvt_pk_bf16(hi[0], hi[1]); w1.y = cvt_pk_bf16(hi[2], hi[3]);
;             *(u32x2*)(p + 4 * n) = w0; *(u32x2*)(p + 32 + 4 * n) = w1; }
;           EPI_FENCE(); }
	v_pk_mul_f32 v[230:231], v[228:229], v[234:235]
	v_pk_mul_f32 v[232:233], v[226:227], v[236:237]
	v_pk_mul_f32 v[234:235], v[222:223], v[234:235]
	v_pk_mul_f32 v[236:237], v[224:225], v[236:237]
	v_pk_fma_f32 v[224:225], v[224:225], v[240:241], v[232:233] neg_lo:[0,0,1] neg_hi:[0,0,1]
	v_pk_fma_f32 v[222:223], v[222:223], v[238:239], v[230:231] neg_lo:[0,0,1] neg_hi:[0,0,1]
	v_pk_fma_f32 v[234:235], v[228:229], v[238:239], v[234:235]
	v_pk_fma_f32 v[236:237], v[226:227], v[240:241], v[236:237]
	v_cvt_pk_bf16_f32 v78, v222, v223
	v_cvt_pk_bf16_f32 v79, v224, v225
	v_cvt_pk_bf16_f32 v70, v234, v235
	v_cvt_pk_bf16_f32 v71, v236, v237
	v_lshlrev_b64 v[230:231], 7, v[160:161]
	v_lshl_add_u64 v[250:251], v[142:143], 0, v[230:231]
	v_lshl_add_u64 v[252:253], v[140:141], 0, v[230:231]
	global_load_dwordx4 v[234:237], v[250:251], off
	global_load_dwordx4 v[238:241], v[252:253], off
	v_cmp_gt_f32_e32 vcc, s85, v196
	v_mul_f32_e32 v220, 0x4b800000, v196
	v_cndmask_b32_e32 v220, v196, v220, vcc
	v_rsq_f32_e32 v220, v220
	v_mul_f32_e32 v221, 0x45800000, v220
	v_cndmask_b32_e32 v220, v220, v221, vcc
	v_pk_mul_f32 v[222:223], v[60:61], v[220:221] op_sel_hi:[1,0]
	v_pk_mul_f32 v[224:225], v[62:63], v[220:221] op_sel_hi:[1,0]
	v_pk_mul_f32 v[228:229], v[52:53], v[220:221] op_sel_hi:[1,0]
	v_pk_mul_f32 v[226:227], v[54:55], v[220:221] op_sel_hi:[1,0]
	s_waitcnt vmcnt(4)
	v_pk_mul_f32 v[230:231], v[228:229], v[242:243]
	v_pk_mul_f32 v[232:233], v[226:227], v[244:245]
	v_pk_mul_f32 v[242:243], v[222:223], v[242:243]
	v_pk_mul_f32 v[244:245], v[224:225], v[244:245]
	v_pk_fma_f32 v[224:225], v[224:225], v[248:249], v[232:233] neg_lo:[0,0,1] neg_hi:[0,0,1]
	v_pk_fma_f32 v[222:223], v[222:223], v[246:247], v[230:231] neg_lo:[0,0,1] neg_hi:[0,0,1]
	v_pk_fma_f32 v[242:243], v[228:229], v[246:247], v[242:243]
	v_pk_fma_f32 v[244:245], v[226:227], v[248:249], v[244:245]
	v_cvt_pk_bf16_f32 v60, v222, v223
	v_cvt_pk_bf16_f32 v61, v224, v225
	v_cvt_pk_bf16_f32 v52, v242, v243
	v_cvt_pk_bf16_f32 v53, v244, v245
	global_load_dwordx4 v[242:245], v[250:251], off offset:16
	global_load_dwordx4 v[246:249], v[252:253], off offset:16
	v_pk_mul_f32 v[222:223], v[56:57], v[220:221] op_sel_hi:[1,0]
	v_pk_mul_f32 v[224:225], v[58:59], v[220:221] op_sel_hi:[1,0]
	v_pk_mul_f32 v[228:229], v[48:49], v[220:221] op_sel_hi:[1,0]
	v_pk_mul_f32 v[226:227], v[50:51], v[220:221] op_sel_hi:[1,0]
	s_waitcnt vmcnt(4)
	v_pk_mul_f32 v[230:231], v[228:229], v[206:207]
	v_pk_mul_f32 v[232:233], v[226:227], v[208:209]
	v_pk_mul_f32 v[206:207], v[222:223], v[206:207]
	v_pk_mul_f32 v[208:209], v[224:225], v[208:209]
	v_pk_fma_f32 v[224:225], v[224:225], v[212:213], v[232:233] neg_lo:[0,0,1] neg_hi:[0,0,1]
	v_pk_fma_f32 v[222:223], v[222:223], v[210:211], v[230:231] neg_lo:[0,0,1] neg_hi:[0,0,1]
	v_pk_fma_f32 v[206:207], v[228:229], v[210:211], v[206:207]
	v_pk_fma_f32 v[208:209], v[226:227], v[212:213], v[208:209]
	v_cvt_pk_bf16_f32 v62, v222, v223
	v_cvt_pk_bf16_f32 v63, v224, v225
	v_cvt_pk_bf16_f32 v54, v206, v207
	v_cvt_pk_bf16_f32 v55, v208, v209
	v_lshlrev_b64 v[230:231], 7, v[158:159]
	v_lshl_add_u64 v[214:215], v[142:143], 0, v[230:231]
	v_lshl_add_u64 v[216:217], v[140:141], 0, v[230:231]
	global_load_dwordx4 v[206:209], v[214:215], off
	global_load_dwordx4 v[210:213], v[216:217], off
	v_cmp_gt_f32_e32 vcc, s85, v195
	v_mul_f32_e32 v220, 0x4b800000, v195
	v_cndmask_b32_e32 v220, v195, v220, vcc
	v_rsq_f32_e32 v220, v220
	v_mul_f32_e32 v221, 0x45800000, v220
	v_cndmask_b32_e32 v220, v220, v221, vcc
	v_pk_mul_f32 v[222:223], v[44:45], v[220:221] op_sel_hi:[1,0]
	v_pk_mul_f32 v[224:225], v[46:47], v[220:221] op_sel_hi:[1,0]
	v_pk_mul_f32 v[228:229], v[36:37], v[220:221] op_sel_hi:[1,0]
	v_pk_mul_f32 v[226:227], v[38:39], v[220:221] op_sel_hi:[1,0]
	s_waitcnt vmcnt(4)
	v_pk_mul_f32 v[230:231], v[228:229], v[234:235]
	v_pk_mul_f32 v[232:233], v[226:227], v[236:237]
	v_pk_mul_f32 v[234:235], v[222:223], v[234:235]
	v_pk_mul_f32 v[236:237], v[224:225], v[236:237]
	v_pk_fma_f32 v[224:225], v[224:225], v[240:241], v[232:233] neg_lo:[0,0,1] neg_hi:[0,0,1]
	v_pk_fma_f32 v[222:223], v[222:223], v[238:239], v[230:231] neg_lo:[0,0,1] neg_hi:[0,0,1]
	v_pk_fma_f32 v[234:235], v[228:229], v[238:239], v[234:235]
	v_pk_fma_f32 v[236:237], v[226:227], v[240:241], v[236:237]
	v_cvt_pk_bf16_f32 v44, v222, v223
	v_cvt_pk_bf16_f32 v45, v224, v225
	v_cvt_pk_bf16_f32 v36, v234, v235
	v_cvt_pk_bf16_f32 v37, v236, v237
	global_load_dwordx4 v[234:237], v[214:215], off offset:16
	global_load_dwordx4 v[238:241], v[216:217], off offset:16
	v_pk_mul_f32 v[222:223], v[40:41], v[220:221] op_sel_hi:[1,0]
	v_pk_mul_f32 v[224:225], v[42:43], v[220:221] op_sel_hi:[1,0]
	v_pk_mul_f32 v[228:229], v[32:33], v[220:221] op_sel_hi:[1,0]
	v_pk_mul_f32 v[226:227], v[34:35], v[220:221] op_sel_hi:[1,0]
	s_waitcnt vmcnt(4)
	v_pk_mul_f32 v[230:231], v[228:229], v[242:243]
	v_pk_mul_f32 v[232:233], v[226:227], v[244:245]
	v_pk_mul_f32 v[242:243], v[222:223], v[242:243]
	v_pk_mul_f32 v[244:245], v[224:225], v[244:245]
	v_pk_fma_f32 v[224:225], v[224:225], v[248:249], v[232:233] neg_lo:[0,0,1] neg_hi:[0,0,1]
	v_pk_fma_f32 v[222:223], v[222:223], v[246:247], v[230:231] neg_lo:[0,0,1] neg_hi:[0,0,1]
	v_pk_fma_f32 v[242:243], v[228:229], v[246:247], v[242:243]
	v_pk_fma_f32 v[244:245], v[226:227], v[248:249], v[244:245]
	v_cvt_pk_bf16_f32 v46, v222, v223
	v_cvt_pk_bf16_f32 v47, v224, v225
	v_cvt_pk_bf16_f32 v38, v242, v243
	v_cvt_pk_bf16_f32 v39, v244, v245
	v_lshlrev_b64 v[230:231], 7, v[156:157]
	v_lshl_add_u64 v[250:251], v[142:143], 0, v[230:231]
	v_lshl_add_u64 v[252:253], v[140:141], 0, v[230:231]
	global_load_dwordx4 v[242:245], v[250:251], off
	global_load_dwordx4 v[246:249], v[252:253], off
	v_fmamk_f32 v221, v194, 0x3b000000, v191
	v_cmp_gt_f32_e32 vcc, s85, v221
	v_mul_f32_e32 v220, 0x4b800000, v221
	v_cndmask_b32_e32 v220, v221, v220, vcc
	v_rsq_f32_e32 v220, v220
	v_mul_f32_e32 v221, 0x45800000, v220
	v_cndmask_b32_e32 v220, v220, v221, vcc
	v_pk_mul_f32 v[222:223], v[28:29], v[220:221] op_sel_hi:[1,0]
	v_pk_mul_f32 v[224:225], v[30:31], v[220:221] op_sel_hi:[1,0]
	v_pk_mul_f32 v[228:229], v[20:21], v[220:221] op_sel_hi:[1,0]
	v_pk_mul_f32 v[226:227], v[22:23], v[220:221] op_sel_hi:[1,0]
	s_waitcnt vmcnt(4)
; __device__ __forceinline__ unsigned cvt_pk_bf16(float lo, float hi) { unsigned r; asm volatile("v_cvt_pk_bf16_f32 %0, %1, %2" : "=v"(r) : "v"(lo), "v"(hi)); return r; }
; #define EPI_FENCE() asm volatile("" ::: "memory")
;   __device__ __forceinline__ void operator()(const AccT& acc, const pg8::Unit& u, int wr, int wc, int fr, int fq) const {
;     ...
;         for (int m = 0; m < 4; ++m) { const int row = row0 + ai * 128 + m * 16; const float r = rsqrtf(rr[ai][m] * (1.f / 512.f) + NORM_EPS);
;           bf16_t* p = qr + (size_t)row * 512 + head * 64 + 8 * fq;
; #pragma unroll
;           for (int n = 0; n < 2; ++n) { const f32x4 c = *(const f32x4*)(cos_r + (size_t)row * 32 + 8 * fq + 4 * n), s = *(const f32x4*)(sin_r + (size_t)row * 32 + 8 * fq + 4 * n);
;             const f32x4 a = acc[ai][0][m][n] * r, b = acc[ai][1][m][n] * r, lo = a * c - b * s, hi = a * s + b * c;
;             u32x2 w0, w1; w0.x = cvt_pk_bf16(lo[0], lo[1]); w0.y = cvt_pk_bf16(lo[2], lo[3]); w1.x = cvt_pk_bf16(hi[0], hi[1]); w1.y = cvt_pk_bf16(hi[2], hi[3]);
;             *(u32x2*)(p + 4 * n) = w0; *(u32x2*)(p + 32 + 4 * n) = w1; }
;           EPI_FENCE(); }
	v_pk_mul_f32 v[230:231], v[228:229], v[206:207]
	v_pk_mul_f32 v[232:233], v[226:227], v[208:209]
	v_pk_mul_f32 v[206:207], v[222:223], v[206:207]
	v_pk_mul_f32 v[208:209], v[224:225], v[208:209]
	v_pk_fma_f32 v[224:225], v[224:225], v[212:213], v[232:233] neg_lo:[0,0,1] neg_hi:[0,0,1]
	v_pk_fma_f32 v[222:223], v[222:223], v[210:211], v[230:231] neg_lo:[0,0,1] neg_hi:[0,0,1]
	v_pk_fma_f32 v[206:207], v[228:229], v[210:211], v[206:207]
	v_pk_fma_f32 v[208:209], v[226:227], v[212:213], v[208:209]
	v_cvt_pk_bf16_f32 v28, v222, v223
	v_cvt_pk_bf16_f32 v29, v224, v225
	v_cvt_pk_bf16_f32 v20, v206, v207
	v_cvt_pk_bf16_f32 v21, v208, v209
	global_load_dwordx4 v[206:209], v[250:251], off offset:16
	global_load_dwordx4 v[210:213], v[252:253], off offset:16
	v_pk_mul_f32 v[222:223], v[24:25], v[220:221] op_sel_hi:[1,0]
	v_pk_mul_f32 v[224:225], v[26:27], v[220:221] op_sel_hi:[1,0]
	v_pk_mul_f32 v[228:229], v[16:17], v[220:221] op_sel_hi:[1,0]
	v_pk_mul_f32 v[226:227], v[18:19], v[220:221] op_sel_hi:[1,0]
	s_waitcnt vmcnt(4)
	v_pk_mul_f32 v[230:231], v[228:229], v[234:235]
	v_pk_mul_f32 v[232:233], v[226:227], v[236:237]
	v_pk_mul_f32 v[234:235], v[222:223], v[234:235]
	v_pk_mul_f32 v[236:237], v[224:225], v[236:237]
	v_pk_fma_f32 v[224:225], v[224:225], v[240:241], v[232:233] neg_lo:[0,0,1] neg_hi:[0,0,1]
	v_pk_fma_f32 v[222:223], v[222:223], v[238:239], v[230:231] neg_lo:[0,0,1] neg_hi:[0,0,1]
	v_pk_fma_f32 v[234:235], v[228:229], v[238:239], v[234:235]
	v_pk_fma_f32 v[236:237], v[226:227], v[240:241], v[236:237]
	v_cvt_pk_bf16_f32 v30, v222, v223
	v_cvt_pk_bf16_f32 v31, v224, v225
	v_cvt_pk_bf16_f32 v22, v234, v235
	v_cvt_pk_bf16_f32 v23, v236, v237
	v_fmamk_f32 v221, v193, 0x3b000000, v191
	v_cmp_gt_f32_e32 vcc, s85, v221
	v_mul_f32_e32 v220, 0x4b800000, v221
	v_cndmask_b32_e32 v220, v221, v220, vcc
	v_rsq_f32_e32 v220, v220
	v_mul_f32_e32 v221, 0x45800000, v220
	v_cndmask_b32_e32 v220, v220, v221, vcc
	v_pk_mul_f32 v[222:223], v[12:13], v[220:221] op_sel_hi:[1,0]
	v_pk_mul_f32 v[224:225], v[14:15], v[220:221] op_sel_hi:[1,0]
	v_pk_mul_f32 v[228:229], v[4:5], v[220:221] op_sel_hi:[1,0]
	v_pk_mul_f32 v[226:227], v[6:7], v[220:221] op_sel_hi:[1,0]
	s_waitcnt vmcnt(2)
	v_pk_mul_f32 v[230:231], v[228:229], v[242:243]
	v_pk_mul_f32 v[232:233], v[226:227], v[244:245]
	v_pk_mul_f32 v[242:243], v[222:223], v[242:243]
	v_pk_mul_f32 v[244:245], v[224:225], v[244:245]
	v_pk_fma_f32 v[224:225], v[224:225], v[248:249], v[232:233] neg_lo:[0,0,1] neg_hi:[0,0,1]
	v_pk_fma_f32 v[222:223], v[222:223], v[246:247], v[230:231] neg_lo:[0,0,1] neg_hi:[0,0,1]
	v_pk_fma_f32 v[242:243], v[228:229], v[246:247], v[242:243]
	v_pk_fma_f32 v[244:245], v[226:227], v[248:249], v[244:245]
	v_cvt_pk_bf16_f32 v12, v222, v223
	v_cvt_pk_bf16_f32 v13, v224, v225
	v_cvt_pk_bf16_f32 v4, v242, v243
	v_cvt_pk_bf16_f32 v5, v244, v245
	v_pk_mul_f32 v[222:223], v[8:9], v[220:221] op_sel_hi:[1,0]
	v_pk_mul_f32 v[224:225], v[10:11], v[220:221] op_sel_hi:[1,0]
	v_pk_mul_f32 v[228:229], v[0:1], v[220:221] op_sel_hi:[1,0]
	v_pk_mul_f32 v[226:227], v[2:3], v[220:221] op_sel_hi:[1,0]
	s_waitcnt vmcnt(0)
	v_pk_mul_f32 v[230:231], v[228:229], v[206:207]
	v_pk_mul_f32 v[232:233], v[226:227], v[208:209]
	v_pk_mul_f32 v[206:207], v[222:223], v[206:207]
	v_pk_mul_f32 v[208:209], v[224:225], v[208:209]
	v_pk_fma_f32 v[224:225], v[224:225], v[212:213], v[232:233] neg_lo:[0,0,1] neg_hi:[0,0,1]
	v_pk_fma_f32 v[222:223], v[222:223], v[210:211], v[230:231] neg_lo:[0,0,1] neg_hi:[0,0,1]
	v_pk_fma_f32 v[206:207], v[228:229], v[210:211], v[206:207]
	v_pk_fma_f32 v[208:209], v[226:227], v[212:213], v[208:209]
	v_cvt_pk_bf16_f32 v14, v222, v223
	v_cvt_pk_bf16_f32 v15, v224, v225
	v_cvt_pk_bf16_f32 v6, v206, v207
	v_cvt_pk_bf16_f32 v7, v208, v209
	v_lshlrev_b64 v[218:219], 10, v[170:171]
	v_lshl_add_u64 v[218:219], s[30:31], 0, v[218:219]
	v_lshl_add_u64 v[218:219], v[218:219], 0, s[48:49]
	v_lshl_add_u64 v[218:219], v[218:219], 0, v[154:155]
	global_store_dwordx4 v[218:219], v[124:127], off
	global_store_dwordx4 v[218:219], v[116:119], off offset:64
	v_lshlrev_b64 v[218:219], 10, v[168:169]
	v_lshl_add_u64 v[218:219], s[30:31], 0, v[218:219]
	v_lshl_add_u64 v[218:219], v[218:219], 0, s[48:49]
	v_lshl_add_u64 v[218:219], v[218:219], 0, v[154:155]
	global_store_dwordx4 v[218:219], v[108:111], off
	global_store_dwordx4 v[218:219], v[100:103], off offset:64
	v_lshlrev_b64 v[218:219], 10, v[166:167]
	v_lshl_add_u64 v[218:219], s[30:31], 0, v[218:219]
	v_lshl_add_u64 v[218:219], v[218:219], 0, s[48:49]
	v_lshl_add_u64 v[218:219], v[218:219], 0, v[154:155]
	global_store_dwordx4 v[218:219], v[92:95], off
	global_store_dwordx4 v[218:219], v[84:87], off offset:64
	v_lshlrev_b64 v[218:219], 10, v[164:165]
	v_lshl_add_u64 v[218:219], s[30:31], 0, v[218:219]
	v_lshl_add_u64 v[218:219], v[218:219], 0, s[48:49]
	v_lshl_add_u64 v[218:219], v[218:219], 0, v[154:155]
	global_store_dwordx4 v[218:219], v[76:79], off
	global_store_dwordx4 v[218:219], v[68:71], off offset:64
	v_lshlrev_b64 v[218:219], 10, v[162:163]
	v_lshl_add_u64 v[218:219], s[30:31], 0, v[218:219]
	v_lshl_add_u64 v[218:219], v[218:219], 0, s[48:49]
	v_lshl_add_u64 v[218:219], v[218:219], 0, v[154:155]
	global_store_dwordx4 v[218:219], v[60:63], off
	global_store_dwordx4 v[218:219], v[52:55], off offset:64
	v_lshlrev_b64 v[218:219], 10, v[160:161]
	v_lshl_add_u64 v[218:219], s[30:31], 0, v[218:219]
	v_lshl_add_u64 v[218:219], v[218:219], 0, s[48:49]
	v_lshl_add_u64 v[218:219], v[218:219], 0, v[154:155]
	global_store_dwordx4 v[218:219], v[44:47], off
	global_store_dwordx4 v[218:219], v[36:39], off offset:64
	v_lshlrev_b64 v[218:219], 10, v[158:159]
	v_lshl_add_u64 v[218:219], s[30:31], 0, v[218:219]
	v_lshl_add_u64 v[218:219], v[218:219], 0, s[48:49]
	v_lshl_add_u64 v[218:219], v[218:219], 0, v[154:155]
	global_store_dwordx4 v[218:219], v[28:31], off
	global_store_dwordx4 v[218:219], v[20:23], off offset:64
	v_lshlrev_b64 v[218:219], 10, v[156:157]
	v_lshl_add_u64 v[218:219], s[30:31], 0, v[218:219]
	v_lshl_add_u64 v[218:219], v[218:219], 0, s[48:49]
	v_lshl_add_u64 v[218:219], v[218:219], 0, v[154:155]
	global_store_dwordx4 v[218:219], v[12:15], off
	global_store_dwordx4 v[218:219], v[4:7], off offset:64
	s_mov_b64 s[48:49], 0
